# adds stage-H decay-row reads hoisted ahead of the running product (BCEG+F)
# baseline (speedup 1.0000x reference)
.LBB0_356:
	s_and_b32 s27, s26, 1
	v_lshl_add_u32 v0, s27, 13, v232
	v_add_u32_e32 v68, 0x800, v0
	ds_read2_b64 v[36:39], v0 offset1:32
	ds_read2_b64 v[72:75], v0 offset0:64 offset1:96
	ds_read2_b64 v[76:79], v0 offset0:128 offset1:160
	ds_read2_b64 v[80:83], v0 offset0:192 offset1:224
	ds_read2_b64 v[84:87], v68 offset1:32
	ds_read2_b64 v[88:91], v68 offset0:64 offset1:96
	ds_read2_b64 v[92:95], v68 offset0:128 offset1:160
	ds_read2_b64 v[96:99], v68 offset0:192 offset1:224
	v_mad_u32_u24 v2, s27, v165, v233
	s_waitcnt lgkmcnt(7)
	v_pk_mul_f32 v[66:67], v[36:37], v[38:39]
	s_waitcnt lgkmcnt(6)
	v_pk_mul_f32 v[64:65], v[66:67], v[72:73]
	s_nop 0
	v_pk_mul_f32 v[60:61], v[64:65], v[74:75]
	s_waitcnt lgkmcnt(5)
	v_pk_mul_f32 v[54:55], v[60:61], v[76:77]
	s_nop 0
	v_pk_mul_f32 v[48:49], v[54:55], v[78:79]
	s_waitcnt lgkmcnt(4)
	v_pk_mul_f32 v[44:45], v[48:49], v[80:81]
	s_nop 0
	v_pk_mul_f32 v[38:39], v[44:45], v[82:83]
	s_waitcnt lgkmcnt(3)
	v_pk_mul_f32 v[58:59], v[38:39], v[84:85]
	v_rcp_f32_e32 v40, v38
	v_pk_mul_f32 v[50:51], v[58:59], v[86:87]
	s_waitcnt lgkmcnt(2)
	v_pk_mul_f32 v[46:47], v[50:51], v[88:89]
	v_rcp_f32_e32 v41, v39
	v_pk_mul_f32 v[42:43], v[46:47], v[90:91]
	s_waitcnt lgkmcnt(1)
	v_pk_mul_f32 v[62:63], v[42:43], v[92:93]
	s_nop 0
	v_pk_mul_f32 v[56:57], v[62:63], v[94:95]
	s_waitcnt lgkmcnt(0)
	v_pk_mul_f32 v[52:53], v[56:57], v[96:97]
	s_nop 0
	v_pk_mul_f32 v[0:1], v[52:53], v[98:99]
	s_and_saveexec_b64 s[28:29], s[4:5]
	s_cbranch_execz .LBB0_358
	v_lshl_add_u32 v74, v177, 1, v2
	ds_read2st64_b32 v[72:73], v74 offset0:96 offset1:112
	ds_read2st64_b32 v[68:69], v74 offset0:64 offset1:80
	v_rcp_f32_e32 v70, v36
	v_rcp_f32_e32 v71, v37
	ds_read_b32 v84, v74 offset:32768
	s_waitcnt lgkmcnt(2)
	v_cvt_f32_f16_e32 v78, v73
	v_cvt_f32_f16_sdwa v79, v73 dst_sel:DWORD dst_unused:UNUSED_PAD src0_sel:WORD_1
	s_waitcnt lgkmcnt(1)
	v_cvt_f32_f16_e32 v74, v68
	v_cvt_f32_f16_sdwa v75, v68 dst_sel:DWORD dst_unused:UNUSED_PAD src0_sel:WORD_1
	v_cvt_f32_f16_e32 v76, v72
	v_cvt_f32_f16_sdwa v77, v72 dst_sel:DWORD dst_unused:UNUSED_PAD src0_sel:WORD_1
	v_cvt_f32_f16_e32 v72, v69
	v_cvt_f32_f16_sdwa v73, v69 dst_sel:DWORD dst_unused:UNUSED_PAD src0_sel:WORD_1
	v_pk_mul_f32 v[78:79], v[36:37], v[78:79]
	v_pk_mul_f32 v[76:77], v[70:71], v[76:77]
	v_pk_mul_f32 v[70:71], v[70:71], v[74:75]
	v_pk_mul_f32 v[72:73], v[40:41], v[72:73]
	v_pk_mul_f32 v[74:75], v[40:41], v[78:79]
	v_cvt_pk_f16_f32 v68, v78, v79
	v_pk_mul_f32 v[80:81], v[38:39], v[76:77]
	v_pk_mul_f32 v[82:83], v[38:39], v[70:71]
	ds_write2st64_b32 v183, v69, v68 offset1:18
	v_cvt_pk_f16_f32 v68, v72, v73
	v_cvt_pk_f16_f32 v69, v74, v75
	v_pk_mul_f32 v[76:77], v[0:1], v[76:77]
	ds_write2st64_b32 v183, v68, v69 offset0:36 offset1:54
	v_cvt_pk_f16_f32 v68, v80, v81
	v_cvt_pk_f16_f32 v69, v82, v83
	ds_write2st64_b32 v183, v68, v69 offset0:72 offset1:90
	v_cvt_f16_f32_e32 v68, v76
	v_pk_mul_f32 v[70:71], v[0:1], v[70:71]
	v_cvt_f16_f32_e32 v69, v77
	v_cvt_f16_f32_e32 v70, v70
	v_cvt_f16_f32_e32 v71, v71
	ds_write_b16 v178, v68
	ds_write_b16 v178, v69 offset:40
	ds_write_b16 v178, v70 offset:5120
	ds_write_b16 v178, v71 offset:5160
	s_waitcnt lgkmcnt(7)
	ds_write_b16 v178, v84 offset:10240
	v_lshl_add_u32 v74, v184, 1, v2
	ds_read2st64_b32 v[68:69], v74 offset0:64 offset1:80
	ds_read2st64_b32 v[72:73], v74 offset0:96 offset1:112
	ds_read_b32 v82, v74 offset:32768
	v_rcp_f32_e32 v70, v66
	v_rcp_f32_e32 v71, v67
	s_waitcnt lgkmcnt(2)
	v_cvt_f32_f16_e32 v76, v69
	v_cvt_f32_f16_sdwa v77, v69 dst_sel:DWORD dst_unused:UNUSED_PAD src0_sel:WORD_1
	s_waitcnt lgkmcnt(1)
	v_cvt_f32_f16_e32 v80, v73
	v_cvt_f32_f16_sdwa v81, v73 dst_sel:DWORD dst_unused:UNUSED_PAD src0_sel:WORD_1
	v_cvt_f32_f16_e32 v74, v68
	v_cvt_f32_f16_e32 v78, v72
	v_cvt_f32_f16_sdwa v79, v72 dst_sel:DWORD dst_unused:UNUSED_PAD src0_sel:WORD_1
	v_cvt_f32_f16_sdwa v75, v68 dst_sel:DWORD dst_unused:UNUSED_PAD src0_sel:WORD_1
	v_pk_mul_f32 v[36:37], v[36:37], v[76:77]
	v_pk_mul_f32 v[68:69], v[66:67], v[80:81]
	v_pk_mul_f32 v[72:73], v[70:71], v[78:79]
	v_pk_mul_f32 v[70:71], v[70:71], v[74:75]
	v_pk_mul_f32 v[74:75], v[40:41], v[36:37]
	v_pk_mul_f32 v[76:77], v[40:41], v[68:69]
	v_cvt_pk_f16_f32 v36, v36, v37
	v_cvt_pk_f16_f32 v37, v68, v69
	v_pk_mul_f32 v[78:79], v[38:39], v[72:73]
	v_pk_mul_f32 v[80:81], v[38:39], v[70:71]
	ds_write2st64_b32 v185, v36, v37 offset1:18
	v_cvt_pk_f16_f32 v36, v74, v75
	v_cvt_pk_f16_f32 v37, v76, v77
	v_pk_mul_f32 v[72:73], v[0:1], v[72:73]
	ds_write2st64_b32 v185, v36, v37 offset0:36 offset1:54
	v_cvt_pk_f16_f32 v36, v78, v79
	v_cvt_pk_f16_f32 v37, v80, v81
	ds_write2st64_b32 v185, v36, v37 offset0:72 offset1:90
	v_cvt_f16_f32_e32 v36, v72
	v_pk_mul_f32 v[70:71], v[0:1], v[70:71]
	v_cvt_f16_f32_e32 v37, v73
	v_cvt_f16_f32_e32 v68, v70
	v_cvt_f16_f32_e32 v69, v71
	ds_write_b16 v178, v36 offset:2
	ds_write_b16 v178, v37 offset:42
	ds_write_b16 v178, v68 offset:5122
	ds_write_b16 v178, v69 offset:5162
	s_waitcnt lgkmcnt(7)
	ds_write_b16 v178, v82 offset:10242
	v_lshl_add_u32 v72, v186, 1, v2
	ds_read2st64_b32 v[36:37], v72 offset0:64 offset1:80
	ds_read2st64_b32 v[70:71], v72 offset0:96 offset1:112
	ds_read_b32 v80, v72 offset:32768
	v_rcp_f32_e32 v68, v64
	v_rcp_f32_e32 v69, v65
	s_waitcnt lgkmcnt(2)
	v_cvt_f32_f16_e32 v74, v37
	v_cvt_f32_f16_sdwa v75, v37 dst_sel:DWORD dst_unused:UNUSED_PAD src0_sel:WORD_1
	s_waitcnt lgkmcnt(1)
	v_cvt_f32_f16_e32 v78, v71
	v_cvt_f32_f16_sdwa v79, v71 dst_sel:DWORD dst_unused:UNUSED_PAD src0_sel:WORD_1
	v_cvt_f32_f16_e32 v72, v36
	v_cvt_f32_f16_e32 v76, v70
	v_cvt_f32_f16_sdwa v77, v70 dst_sel:DWORD dst_unused:UNUSED_PAD src0_sel:WORD_1
	v_cvt_f32_f16_sdwa v73, v36 dst_sel:DWORD dst_unused:UNUSED_PAD src0_sel:WORD_1
	v_pk_mul_f32 v[36:37], v[66:67], v[74:75]
	v_pk_mul_f32 v[66:67], v[64:65], v[78:79]
	v_pk_mul_f32 v[70:71], v[68:69], v[76:77]
	v_pk_mul_f32 v[68:69], v[68:69], v[72:73]
	v_pk_mul_f32 v[72:73], v[40:41], v[36:37]
	v_pk_mul_f32 v[74:75], v[40:41], v[66:67]
	v_cvt_pk_f16_f32 v36, v36, v37
	v_cvt_pk_f16_f32 v37, v66, v67
	v_pk_mul_f32 v[76:77], v[38:39], v[70:71]
	v_pk_mul_f32 v[78:79], v[38:39], v[68:69]
	ds_write2st64_b32 v187, v36, v37 offset1:18
	v_cvt_pk_f16_f32 v36, v72, v73
	v_cvt_pk_f16_f32 v37, v74, v75
	v_pk_mul_f32 v[70:71], v[0:1], v[70:71]
	ds_write2st64_b32 v187, v36, v37 offset0:36 offset1:54
	v_cvt_pk_f16_f32 v36, v76, v77
	v_cvt_pk_f16_f32 v37, v78, v79
	ds_write2st64_b32 v187, v36, v37 offset0:72 offset1:90
	v_cvt_f16_f32_e32 v36, v70
	v_pk_mul_f32 v[68:69], v[0:1], v[68:69]
	v_cvt_f16_f32_e32 v37, v71
	v_cvt_f16_f32_e32 v66, v68
	v_cvt_f16_f32_e32 v67, v69
	ds_write_b16 v178, v36 offset:4
	ds_write_b16 v178, v37 offset:44
	ds_write_b16 v178, v66 offset:5124
	ds_write_b16 v178, v67 offset:5164
	s_waitcnt lgkmcnt(7)
	ds_write_b16 v178, v80 offset:10244
	v_lshl_add_u32 v70, v188, 1, v2
	ds_read2st64_b32 v[36:37], v70 offset0:64 offset1:80
	ds_read2st64_b32 v[68:69], v70 offset0:96 offset1:112
	ds_read_b32 v78, v70 offset:32768
	v_rcp_f32_e32 v66, v60
	v_rcp_f32_e32 v67, v61
	s_waitcnt lgkmcnt(2)
	v_cvt_f32_f16_e32 v72, v37
	v_cvt_f32_f16_sdwa v73, v37 dst_sel:DWORD dst_unused:UNUSED_PAD src0_sel:WORD_1
	s_waitcnt lgkmcnt(1)
	v_cvt_f32_f16_e32 v76, v69
	v_cvt_f32_f16_sdwa v77, v69 dst_sel:DWORD dst_unused:UNUSED_PAD src0_sel:WORD_1
	v_cvt_f32_f16_e32 v70, v36
	v_cvt_f32_f16_e32 v74, v68
	v_cvt_f32_f16_sdwa v75, v68 dst_sel:DWORD dst_unused:UNUSED_PAD src0_sel:WORD_1
	v_cvt_f32_f16_sdwa v71, v36 dst_sel:DWORD dst_unused:UNUSED_PAD src0_sel:WORD_1
	v_pk_mul_f32 v[36:37], v[64:65], v[72:73]
	v_pk_mul_f32 v[64:65], v[60:61], v[76:77]
	v_pk_mul_f32 v[68:69], v[66:67], v[74:75]
	v_pk_mul_f32 v[66:67], v[66:67], v[70:71]
	v_pk_mul_f32 v[70:71], v[40:41], v[36:37]
	v_pk_mul_f32 v[72:73], v[40:41], v[64:65]
	v_cvt_pk_f16_f32 v36, v36, v37
	v_cvt_pk_f16_f32 v37, v64, v65
	v_pk_mul_f32 v[74:75], v[38:39], v[68:69]
	v_pk_mul_f32 v[76:77], v[38:39], v[66:67]
	ds_write2st64_b32 v189, v36, v37 offset1:18
	v_cvt_pk_f16_f32 v36, v70, v71
	v_cvt_pk_f16_f32 v37, v72, v73
	v_pk_mul_f32 v[68:69], v[0:1], v[68:69]
	ds_write2st64_b32 v189, v36, v37 offset0:36 offset1:54
	v_cvt_pk_f16_f32 v36, v74, v75
	v_cvt_pk_f16_f32 v37, v76, v77
	ds_write2st64_b32 v189, v36, v37 offset0:72 offset1:90
	v_cvt_f16_f32_e32 v36, v68
	v_pk_mul_f32 v[66:67], v[0:1], v[66:67]
	v_cvt_f16_f32_e32 v37, v69
	v_cvt_f16_f32_e32 v64, v66
	v_cvt_f16_f32_e32 v65, v67
	ds_write_b16 v178, v36 offset:6
	ds_write_b16 v178, v37 offset:46
	ds_write_b16 v178, v64 offset:5126
	ds_write_b16 v178, v65 offset:5166
	s_waitcnt lgkmcnt(7)
	ds_write_b16 v178, v78 offset:10246
	v_perm_b32 v36, v82, v84, s82
	v_perm_b32 v37, v78, v80, s82
	ds_write_b64 v178, v[36:37] offset:10280

.LBB0_455:
	s_andn2_b64 vcc, exec, s[24:25]
	s_mov_b64 s[26:27], -1
	s_cbranch_vccnz .LBB0_463
	s_and_b32 s26, s76, 1
	v_lshl_add_u32 v0, s26, 13, v227
	v_add_u32_e32 v68, 0x800, v0
	ds_read2_b64 v[36:39], v0 offset1:32
	ds_read2_b64 v[72:75], v0 offset0:64 offset1:96
	ds_read2_b64 v[76:79], v0 offset0:128 offset1:160
	ds_read2_b64 v[80:83], v0 offset0:192 offset1:224
	ds_read2_b64 v[84:87], v68 offset1:32
	ds_read2_b64 v[88:91], v68 offset0:64 offset1:96
	ds_read2_b64 v[92:95], v68 offset0:128 offset1:160
	ds_read2_b64 v[96:99], v68 offset0:192 offset1:224
	v_mad_u32_u24 v2, s26, v165, v228
	s_waitcnt lgkmcnt(7)
	v_pk_mul_f32 v[66:67], v[36:37], v[38:39]
	s_waitcnt lgkmcnt(6)
	v_pk_mul_f32 v[64:65], v[66:67], v[72:73]
	s_nop 0
	v_pk_mul_f32 v[60:61], v[64:65], v[74:75]
	s_waitcnt lgkmcnt(5)
	v_pk_mul_f32 v[54:55], v[60:61], v[76:77]
	s_nop 0
	v_pk_mul_f32 v[48:49], v[54:55], v[78:79]
	s_waitcnt lgkmcnt(4)
	v_pk_mul_f32 v[44:45], v[48:49], v[80:81]
	s_nop 0
	v_pk_mul_f32 v[38:39], v[44:45], v[82:83]
	s_waitcnt lgkmcnt(3)
	v_pk_mul_f32 v[58:59], v[38:39], v[84:85]
	v_rcp_f32_e32 v40, v38
	v_pk_mul_f32 v[50:51], v[58:59], v[86:87]
	s_waitcnt lgkmcnt(2)
	v_pk_mul_f32 v[46:47], v[50:51], v[88:89]
	v_rcp_f32_e32 v41, v39
	v_pk_mul_f32 v[42:43], v[46:47], v[90:91]
	s_waitcnt lgkmcnt(1)
	v_pk_mul_f32 v[62:63], v[42:43], v[92:93]
	s_nop 0
	v_pk_mul_f32 v[56:57], v[62:63], v[94:95]
	s_waitcnt lgkmcnt(0)
	v_pk_mul_f32 v[52:53], v[56:57], v[96:97]
	s_nop 0
	v_pk_mul_f32 v[0:1], v[52:53], v[98:99]
	s_and_saveexec_b64 s[26:27], s[4:5]
	s_cbranch_execz .LBB0_458
	v_lshl_add_u32 v74, v173, 1, v2
	ds_read2st64_b32 v[72:73], v74 offset0:96 offset1:112
	ds_read2st64_b32 v[68:69], v74 offset0:64 offset1:80
	v_rcp_f32_e32 v70, v36
	v_rcp_f32_e32 v71, v37
	ds_read_b32 v84, v74 offset:32768
	s_waitcnt lgkmcnt(2)
	v_cvt_f32_f16_e32 v78, v73
	v_cvt_f32_f16_sdwa v79, v73 dst_sel:DWORD dst_unused:UNUSED_PAD src0_sel:WORD_1
	s_waitcnt lgkmcnt(1)
	v_cvt_f32_f16_e32 v74, v68
	v_cvt_f32_f16_sdwa v75, v68 dst_sel:DWORD dst_unused:UNUSED_PAD src0_sel:WORD_1
	v_cvt_f32_f16_e32 v76, v72
	v_cvt_f32_f16_sdwa v77, v72 dst_sel:DWORD dst_unused:UNUSED_PAD src0_sel:WORD_1
	v_cvt_f32_f16_e32 v72, v69
	v_cvt_f32_f16_sdwa v73, v69 dst_sel:DWORD dst_unused:UNUSED_PAD src0_sel:WORD_1
	v_pk_mul_f32 v[78:79], v[36:37], v[78:79]
	v_pk_mul_f32 v[76:77], v[70:71], v[76:77]
	v_pk_mul_f32 v[70:71], v[70:71], v[74:75]
	v_pk_mul_f32 v[72:73], v[40:41], v[72:73]
	v_pk_mul_f32 v[74:75], v[40:41], v[78:79]
	v_cvt_pk_f16_f32 v68, v78, v79
	v_pk_mul_f32 v[80:81], v[38:39], v[76:77]
	v_pk_mul_f32 v[82:83], v[38:39], v[70:71]
	ds_write2st64_b32 v179, v69, v68 offset1:18
	v_cvt_pk_f16_f32 v68, v72, v73
	v_cvt_pk_f16_f32 v69, v74, v75
	v_pk_mul_f32 v[76:77], v[0:1], v[76:77]
	ds_write2st64_b32 v179, v68, v69 offset0:36 offset1:54
	v_cvt_pk_f16_f32 v68, v80, v81
	v_cvt_pk_f16_f32 v69, v82, v83
	ds_write2st64_b32 v179, v68, v69 offset0:72 offset1:90
	v_cvt_f16_f32_e32 v68, v76
	v_pk_mul_f32 v[70:71], v[0:1], v[70:71]
	v_cvt_f16_f32_e32 v69, v77
	v_cvt_f16_f32_e32 v70, v70
	v_cvt_f16_f32_e32 v71, v71
	ds_write_b16 v174, v68
	ds_write_b16 v174, v69 offset:40
	ds_write_b16 v174, v70 offset:5120
	ds_write_b16 v174, v71 offset:5160
	s_waitcnt lgkmcnt(7)
	ds_write_b16 v174, v84 offset:10240
	v_lshl_add_u32 v74, v180, 1, v2
	ds_read2st64_b32 v[68:69], v74 offset0:64 offset1:80
	ds_read2st64_b32 v[72:73], v74 offset0:96 offset1:112
	ds_read_b32 v82, v74 offset:32768
	v_rcp_f32_e32 v70, v66
	v_rcp_f32_e32 v71, v67
	s_waitcnt lgkmcnt(2)
	v_cvt_f32_f16_e32 v76, v69
	v_cvt_f32_f16_sdwa v77, v69 dst_sel:DWORD dst_unused:UNUSED_PAD src0_sel:WORD_1
	s_waitcnt lgkmcnt(1)
	v_cvt_f32_f16_e32 v80, v73
	v_cvt_f32_f16_sdwa v81, v73 dst_sel:DWORD dst_unused:UNUSED_PAD src0_sel:WORD_1
	v_cvt_f32_f16_e32 v74, v68
	v_cvt_f32_f16_e32 v78, v72
	v_cvt_f32_f16_sdwa v79, v72 dst_sel:DWORD dst_unused:UNUSED_PAD src0_sel:WORD_1
	v_cvt_f32_f16_sdwa v75, v68 dst_sel:DWORD dst_unused:UNUSED_PAD src0_sel:WORD_1
	v_pk_mul_f32 v[36:37], v[36:37], v[76:77]
	v_pk_mul_f32 v[68:69], v[66:67], v[80:81]
	v_pk_mul_f32 v[72:73], v[70:71], v[78:79]
	v_pk_mul_f32 v[70:71], v[70:71], v[74:75]
	v_pk_mul_f32 v[74:75], v[40:41], v[36:37]
	v_pk_mul_f32 v[76:77], v[40:41], v[68:69]
	v_cvt_pk_f16_f32 v36, v36, v37
	v_cvt_pk_f16_f32 v37, v68, v69
	v_pk_mul_f32 v[78:79], v[38:39], v[72:73]
	v_pk_mul_f32 v[80:81], v[38:39], v[70:71]
	ds_write2st64_b32 v181, v36, v37 offset1:18
	v_cvt_pk_f16_f32 v36, v74, v75
	v_cvt_pk_f16_f32 v37, v76, v77
	v_pk_mul_f32 v[72:73], v[0:1], v[72:73]
	ds_write2st64_b32 v181, v36, v37 offset0:36 offset1:54
	v_cvt_pk_f16_f32 v36, v78, v79
	v_cvt_pk_f16_f32 v37, v80, v81
	ds_write2st64_b32 v181, v36, v37 offset0:72 offset1:90
	v_cvt_f16_f32_e32 v36, v72
	v_pk_mul_f32 v[70:71], v[0:1], v[70:71]
	v_cvt_f16_f32_e32 v37, v73
	v_cvt_f16_f32_e32 v68, v70
	v_cvt_f16_f32_e32 v69, v71
	ds_write_b16 v174, v36 offset:2
	ds_write_b16 v174, v37 offset:42
	ds_write_b16 v174, v68 offset:5122
	ds_write_b16 v174, v69 offset:5162
	s_waitcnt lgkmcnt(7)
	ds_write_b16 v174, v82 offset:10242
	v_lshl_add_u32 v72, v182, 1, v2
	ds_read2st64_b32 v[36:37], v72 offset0:64 offset1:80
	ds_read2st64_b32 v[70:71], v72 offset0:96 offset1:112
	ds_read_b32 v80, v72 offset:32768
	v_rcp_f32_e32 v68, v64
	v_rcp_f32_e32 v69, v65
	s_waitcnt lgkmcnt(2)
	v_cvt_f32_f16_e32 v74, v37
	v_cvt_f32_f16_sdwa v75, v37 dst_sel:DWORD dst_unused:UNUSED_PAD src0_sel:WORD_1
	s_waitcnt lgkmcnt(1)
	v_cvt_f32_f16_e32 v78, v71
	v_cvt_f32_f16_sdwa v79, v71 dst_sel:DWORD dst_unused:UNUSED_PAD src0_sel:WORD_1
	v_cvt_f32_f16_e32 v72, v36
	v_cvt_f32_f16_e32 v76, v70
	v_cvt_f32_f16_sdwa v77, v70 dst_sel:DWORD dst_unused:UNUSED_PAD src0_sel:WORD_1
	v_cvt_f32_f16_sdwa v73, v36 dst_sel:DWORD dst_unused:UNUSED_PAD src0_sel:WORD_1
	v_pk_mul_f32 v[36:37], v[66:67], v[74:75]
	v_pk_mul_f32 v[66:67], v[64:65], v[78:79]
	v_pk_mul_f32 v[70:71], v[68:69], v[76:77]
	v_pk_mul_f32 v[68:69], v[68:69], v[72:73]
	v_pk_mul_f32 v[72:73], v[40:41], v[36:37]
	v_pk_mul_f32 v[74:75], v[40:41], v[66:67]
	v_cvt_pk_f16_f32 v36, v36, v37
	v_cvt_pk_f16_f32 v37, v66, v67
	v_pk_mul_f32 v[76:77], v[38:39], v[70:71]
	v_pk_mul_f32 v[78:79], v[38:39], v[68:69]
	ds_write2st64_b32 v183, v36, v37 offset1:18
	v_cvt_pk_f16_f32 v36, v72, v73
	v_cvt_pk_f16_f32 v37, v74, v75
	v_pk_mul_f32 v[70:71], v[0:1], v[70:71]
	ds_write2st64_b32 v183, v36, v37 offset0:36 offset1:54
	v_cvt_pk_f16_f32 v36, v76, v77
	v_cvt_pk_f16_f32 v37, v78, v79
	ds_write2st64_b32 v183, v36, v37 offset0:72 offset1:90
	v_cvt_f16_f32_e32 v36, v70
	v_pk_mul_f32 v[68:69], v[0:1], v[68:69]
	v_cvt_f16_f32_e32 v37, v71
	v_cvt_f16_f32_e32 v66, v68
	v_cvt_f16_f32_e32 v67, v69
	ds_write_b16 v174, v36 offset:4
	ds_write_b16 v174, v37 offset:44
	ds_write_b16 v174, v66 offset:5124
	ds_write_b16 v174, v67 offset:5164
	s_waitcnt lgkmcnt(7)
	ds_write_b16 v174, v80 offset:10244
	v_lshl_add_u32 v70, v184, 1, v2
	ds_read2st64_b32 v[36:37], v70 offset0:64 offset1:80
	ds_read2st64_b32 v[68:69], v70 offset0:96 offset1:112
	ds_read_b32 v78, v70 offset:32768
	v_rcp_f32_e32 v66, v60
	v_rcp_f32_e32 v67, v61
	s_waitcnt lgkmcnt(2)
	v_cvt_f32_f16_e32 v72, v37
	v_cvt_f32_f16_sdwa v73, v37 dst_sel:DWORD dst_unused:UNUSED_PAD src0_sel:WORD_1
	s_waitcnt lgkmcnt(1)
	v_cvt_f32_f16_e32 v76, v69
	v_cvt_f32_f16_sdwa v77, v69 dst_sel:DWORD dst_unused:UNUSED_PAD src0_sel:WORD_1
	v_cvt_f32_f16_e32 v70, v36
	v_cvt_f32_f16_e32 v74, v68
	v_cvt_f32_f16_sdwa v75, v68 dst_sel:DWORD dst_unused:UNUSED_PAD src0_sel:WORD_1
	v_cvt_f32_f16_sdwa v71, v36 dst_sel:DWORD dst_unused:UNUSED_PAD src0_sel:WORD_1
	v_pk_mul_f32 v[36:37], v[64:65], v[72:73]
	v_pk_mul_f32 v[64:65], v[60:61], v[76:77]
	v_pk_mul_f32 v[68:69], v[66:67], v[74:75]
	v_pk_mul_f32 v[66:67], v[66:67], v[70:71]
	v_pk_mul_f32 v[70:71], v[40:41], v[36:37]
	v_pk_mul_f32 v[72:73], v[40:41], v[64:65]
	v_cvt_pk_f16_f32 v36, v36, v37
	v_cvt_pk_f16_f32 v37, v64, v65
	v_pk_mul_f32 v[74:75], v[38:39], v[68:69]
	v_pk_mul_f32 v[76:77], v[38:39], v[66:67]
	ds_write2st64_b32 v185, v36, v37 offset1:18
	v_cvt_pk_f16_f32 v36, v70, v71
	v_cvt_pk_f16_f32 v37, v72, v73
	v_pk_mul_f32 v[68:69], v[0:1], v[68:69]
	ds_write2st64_b32 v185, v36, v37 offset0:36 offset1:54
	v_cvt_pk_f16_f32 v36, v74, v75
	v_cvt_pk_f16_f32 v37, v76, v77
	ds_write2st64_b32 v185, v36, v37 offset0:72 offset1:90
	v_cvt_f16_f32_e32 v36, v68
	v_pk_mul_f32 v[66:67], v[0:1], v[66:67]
	v_cvt_f16_f32_e32 v37, v69
	v_cvt_f16_f32_e32 v64, v66
	v_cvt_f16_f32_e32 v65, v67
	ds_write_b16 v174, v36 offset:6
	ds_write_b16 v174, v37 offset:46
	ds_write_b16 v174, v64 offset:5126
	ds_write_b16 v174, v65 offset:5166
	s_waitcnt lgkmcnt(7)
	ds_write_b16 v174, v78 offset:10246
	v_perm_b32 v36, v82, v84, s82
	v_perm_b32 v37, v78, v80, s82
	ds_write_b64 v174, v[36:37] offset:10280

.LBB0_929:
	s_and_b32 s27, s26, 1
	v_lshl_add_u32 v0, s27, 13, v234
	v_add_u32_e32 v68, 0x800, v0
	ds_read2_b64 v[36:39], v0 offset1:32
	ds_read2_b64 v[72:75], v0 offset0:64 offset1:96
	ds_read2_b64 v[76:79], v0 offset0:128 offset1:160
	ds_read2_b64 v[80:83], v0 offset0:192 offset1:224
	ds_read2_b64 v[84:87], v68 offset1:32
	ds_read2_b64 v[88:91], v68 offset0:64 offset1:96
	ds_read2_b64 v[92:95], v68 offset0:128 offset1:160
	ds_read2_b64 v[96:99], v68 offset0:192 offset1:224
	v_mad_u32_u24 v2, s27, v167, v235
	s_waitcnt lgkmcnt(7)
	v_pk_mul_f32 v[66:67], v[36:37], v[38:39]
	s_waitcnt lgkmcnt(6)
	v_pk_mul_f32 v[64:65], v[66:67], v[72:73]
	s_nop 0
	v_pk_mul_f32 v[60:61], v[64:65], v[74:75]
	s_waitcnt lgkmcnt(5)
	v_pk_mul_f32 v[54:55], v[60:61], v[76:77]
	s_nop 0
	v_pk_mul_f32 v[48:49], v[54:55], v[78:79]
	s_waitcnt lgkmcnt(4)
	v_pk_mul_f32 v[44:45], v[48:49], v[80:81]
	s_nop 0
	v_pk_mul_f32 v[38:39], v[44:45], v[82:83]
	s_waitcnt lgkmcnt(3)
	v_pk_mul_f32 v[58:59], v[38:39], v[84:85]
	v_rcp_f32_e32 v40, v38
	v_pk_mul_f32 v[50:51], v[58:59], v[86:87]
	s_waitcnt lgkmcnt(2)
	v_pk_mul_f32 v[46:47], v[50:51], v[88:89]
	v_rcp_f32_e32 v41, v39
	v_pk_mul_f32 v[42:43], v[46:47], v[90:91]
	s_waitcnt lgkmcnt(1)
	v_pk_mul_f32 v[62:63], v[42:43], v[92:93]
	s_nop 0
	v_pk_mul_f32 v[56:57], v[62:63], v[94:95]
	s_waitcnt lgkmcnt(0)
	v_pk_mul_f32 v[52:53], v[56:57], v[96:97]
	s_nop 0
	v_pk_mul_f32 v[0:1], v[52:53], v[98:99]
	s_and_saveexec_b64 s[28:29], s[4:5]
	s_cbranch_execz .LBB0_931
	v_lshl_add_u32 v74, v179, 1, v2
	ds_read2st64_b32 v[72:73], v74 offset0:96 offset1:112
	ds_read2st64_b32 v[68:69], v74 offset0:64 offset1:80
	v_rcp_f32_e32 v70, v36
	v_rcp_f32_e32 v71, v37
	ds_read_b32 v84, v74 offset:32768
	s_waitcnt lgkmcnt(2)
	v_cvt_f32_f16_e32 v78, v73
	v_cvt_f32_f16_sdwa v79, v73 dst_sel:DWORD dst_unused:UNUSED_PAD src0_sel:WORD_1
	s_waitcnt lgkmcnt(1)
	v_cvt_f32_f16_e32 v74, v68
	v_cvt_f32_f16_sdwa v75, v68 dst_sel:DWORD dst_unused:UNUSED_PAD src0_sel:WORD_1
	v_cvt_f32_f16_e32 v76, v72
	v_cvt_f32_f16_sdwa v77, v72 dst_sel:DWORD dst_unused:UNUSED_PAD src0_sel:WORD_1
	v_cvt_f32_f16_e32 v72, v69
	v_cvt_f32_f16_sdwa v73, v69 dst_sel:DWORD dst_unused:UNUSED_PAD src0_sel:WORD_1
	v_pk_mul_f32 v[78:79], v[36:37], v[78:79]
	v_pk_mul_f32 v[76:77], v[70:71], v[76:77]
	v_pk_mul_f32 v[70:71], v[70:71], v[74:75]
	v_pk_mul_f32 v[72:73], v[40:41], v[72:73]
	v_pk_mul_f32 v[74:75], v[40:41], v[78:79]
	v_cvt_pk_f16_f32 v68, v78, v79
	v_pk_mul_f32 v[80:81], v[38:39], v[76:77]
	v_pk_mul_f32 v[82:83], v[38:39], v[70:71]
	ds_write2st64_b32 v185, v69, v68 offset1:18
	v_cvt_pk_f16_f32 v68, v72, v73
	v_cvt_pk_f16_f32 v69, v74, v75
	v_pk_mul_f32 v[76:77], v[0:1], v[76:77]
	ds_write2st64_b32 v185, v68, v69 offset0:36 offset1:54
	v_cvt_pk_f16_f32 v68, v80, v81
	v_cvt_pk_f16_f32 v69, v82, v83
	ds_write2st64_b32 v185, v68, v69 offset0:72 offset1:90
	v_cvt_f16_f32_e32 v68, v76
	v_pk_mul_f32 v[70:71], v[0:1], v[70:71]
	v_cvt_f16_f32_e32 v69, v77
	v_cvt_f16_f32_e32 v70, v70
	v_cvt_f16_f32_e32 v71, v71
	ds_write_b16 v180, v68
	ds_write_b16 v180, v69 offset:40
	ds_write_b16 v180, v70 offset:5120
	ds_write_b16 v180, v71 offset:5160
	s_waitcnt lgkmcnt(7)
	ds_write_b16 v180, v84 offset:10240
	v_lshl_add_u32 v74, v186, 1, v2
	ds_read2st64_b32 v[68:69], v74 offset0:64 offset1:80
	ds_read2st64_b32 v[72:73], v74 offset0:96 offset1:112
	ds_read_b32 v82, v74 offset:32768
	v_rcp_f32_e32 v70, v66
	v_rcp_f32_e32 v71, v67
	s_waitcnt lgkmcnt(2)
	v_cvt_f32_f16_e32 v76, v69
	v_cvt_f32_f16_sdwa v77, v69 dst_sel:DWORD dst_unused:UNUSED_PAD src0_sel:WORD_1
	s_waitcnt lgkmcnt(1)
	v_cvt_f32_f16_e32 v80, v73
	v_cvt_f32_f16_sdwa v81, v73 dst_sel:DWORD dst_unused:UNUSED_PAD src0_sel:WORD_1
	v_cvt_f32_f16_e32 v74, v68
	v_cvt_f32_f16_e32 v78, v72
	v_cvt_f32_f16_sdwa v79, v72 dst_sel:DWORD dst_unused:UNUSED_PAD src0_sel:WORD_1
	v_cvt_f32_f16_sdwa v75, v68 dst_sel:DWORD dst_unused:UNUSED_PAD src0_sel:WORD_1
	v_pk_mul_f32 v[36:37], v[36:37], v[76:77]
	v_pk_mul_f32 v[68:69], v[66:67], v[80:81]
	v_pk_mul_f32 v[72:73], v[70:71], v[78:79]
	v_pk_mul_f32 v[70:71], v[70:71], v[74:75]
	v_pk_mul_f32 v[74:75], v[40:41], v[36:37]
	v_pk_mul_f32 v[76:77], v[40:41], v[68:69]
	v_cvt_pk_f16_f32 v36, v36, v37
	v_cvt_pk_f16_f32 v37, v68, v69
	v_pk_mul_f32 v[78:79], v[38:39], v[72:73]
	v_pk_mul_f32 v[80:81], v[38:39], v[70:71]
	ds_write2st64_b32 v187, v36, v37 offset1:18
	v_cvt_pk_f16_f32 v36, v74, v75
	v_cvt_pk_f16_f32 v37, v76, v77
	v_pk_mul_f32 v[72:73], v[0:1], v[72:73]
	ds_write2st64_b32 v187, v36, v37 offset0:36 offset1:54
	v_cvt_pk_f16_f32 v36, v78, v79
	v_cvt_pk_f16_f32 v37, v80, v81
	ds_write2st64_b32 v187, v36, v37 offset0:72 offset1:90
	v_cvt_f16_f32_e32 v36, v72
	v_pk_mul_f32 v[70:71], v[0:1], v[70:71]
	v_cvt_f16_f32_e32 v37, v73
	v_cvt_f16_f32_e32 v68, v70
	v_cvt_f16_f32_e32 v69, v71
	ds_write_b16 v180, v36 offset:2
	ds_write_b16 v180, v37 offset:42
	ds_write_b16 v180, v68 offset:5122
	ds_write_b16 v180, v69 offset:5162
	s_waitcnt lgkmcnt(7)
	ds_write_b16 v180, v82 offset:10242
	v_lshl_add_u32 v72, v188, 1, v2
	ds_read2st64_b32 v[36:37], v72 offset0:64 offset1:80
	ds_read2st64_b32 v[70:71], v72 offset0:96 offset1:112
	ds_read_b32 v80, v72 offset:32768
	v_rcp_f32_e32 v68, v64
	v_rcp_f32_e32 v69, v65
	s_waitcnt lgkmcnt(2)
	v_cvt_f32_f16_e32 v74, v37
	v_cvt_f32_f16_sdwa v75, v37 dst_sel:DWORD dst_unused:UNUSED_PAD src0_sel:WORD_1
	s_waitcnt lgkmcnt(1)
	v_cvt_f32_f16_e32 v78, v71
	v_cvt_f32_f16_sdwa v79, v71 dst_sel:DWORD dst_unused:UNUSED_PAD src0_sel:WORD_1
	v_cvt_f32_f16_e32 v72, v36
	v_cvt_f32_f16_e32 v76, v70
	v_cvt_f32_f16_sdwa v77, v70 dst_sel:DWORD dst_unused:UNUSED_PAD src0_sel:WORD_1
	v_cvt_f32_f16_sdwa v73, v36 dst_sel:DWORD dst_unused:UNUSED_PAD src0_sel:WORD_1
	v_pk_mul_f32 v[36:37], v[66:67], v[74:75]
	v_pk_mul_f32 v[66:67], v[64:65], v[78:79]
	v_pk_mul_f32 v[70:71], v[68:69], v[76:77]
	v_pk_mul_f32 v[68:69], v[68:69], v[72:73]
	v_pk_mul_f32 v[72:73], v[40:41], v[36:37]
	v_pk_mul_f32 v[74:75], v[40:41], v[66:67]
	v_cvt_pk_f16_f32 v36, v36, v37
	v_cvt_pk_f16_f32 v37, v66, v67
	v_pk_mul_f32 v[76:77], v[38:39], v[70:71]
	v_pk_mul_f32 v[78:79], v[38:39], v[68:69]
	ds_write2st64_b32 v189, v36, v37 offset1:18
	v_cvt_pk_f16_f32 v36, v72, v73
	v_cvt_pk_f16_f32 v37, v74, v75
	v_pk_mul_f32 v[70:71], v[0:1], v[70:71]
	ds_write2st64_b32 v189, v36, v37 offset0:36 offset1:54
	v_cvt_pk_f16_f32 v36, v76, v77
	v_cvt_pk_f16_f32 v37, v78, v79
	ds_write2st64_b32 v189, v36, v37 offset0:72 offset1:90
	v_cvt_f16_f32_e32 v36, v70
	v_pk_mul_f32 v[68:69], v[0:1], v[68:69]
	v_cvt_f16_f32_e32 v37, v71
	v_cvt_f16_f32_e32 v66, v68
	v_cvt_f16_f32_e32 v67, v69
	ds_write_b16 v180, v36 offset:4
	ds_write_b16 v180, v37 offset:44
	ds_write_b16 v180, v66 offset:5124
	ds_write_b16 v180, v67 offset:5164
	s_waitcnt lgkmcnt(7)
	ds_write_b16 v180, v80 offset:10244
	v_lshl_add_u32 v70, v190, 1, v2
	ds_read2st64_b32 v[36:37], v70 offset0:64 offset1:80
	ds_read2st64_b32 v[68:69], v70 offset0:96 offset1:112
	ds_read_b32 v78, v70 offset:32768
	v_rcp_f32_e32 v66, v60
	v_rcp_f32_e32 v67, v61
	s_waitcnt lgkmcnt(2)
	v_cvt_f32_f16_e32 v72, v37
	v_cvt_f32_f16_sdwa v73, v37 dst_sel:DWORD dst_unused:UNUSED_PAD src0_sel:WORD_1
	s_waitcnt lgkmcnt(1)
	v_cvt_f32_f16_e32 v76, v69
	v_cvt_f32_f16_sdwa v77, v69 dst_sel:DWORD dst_unused:UNUSED_PAD src0_sel:WORD_1
	v_cvt_f32_f16_e32 v70, v36
	v_cvt_f32_f16_e32 v74, v68
	v_cvt_f32_f16_sdwa v75, v68 dst_sel:DWORD dst_unused:UNUSED_PAD src0_sel:WORD_1
	v_cvt_f32_f16_sdwa v71, v36 dst_sel:DWORD dst_unused:UNUSED_PAD src0_sel:WORD_1
	v_pk_mul_f32 v[36:37], v[64:65], v[72:73]
	v_pk_mul_f32 v[64:65], v[60:61], v[76:77]
	v_pk_mul_f32 v[68:69], v[66:67], v[74:75]
	v_pk_mul_f32 v[66:67], v[66:67], v[70:71]
	v_pk_mul_f32 v[70:71], v[40:41], v[36:37]
	v_pk_mul_f32 v[72:73], v[40:41], v[64:65]
	v_cvt_pk_f16_f32 v36, v36, v37
	v_cvt_pk_f16_f32 v37, v64, v65
	v_pk_mul_f32 v[74:75], v[38:39], v[68:69]
	v_pk_mul_f32 v[76:77], v[38:39], v[66:67]
	ds_write2st64_b32 v191, v36, v37 offset1:18
	v_cvt_pk_f16_f32 v36, v70, v71
	v_cvt_pk_f16_f32 v37, v72, v73
	v_pk_mul_f32 v[68:69], v[0:1], v[68:69]
	ds_write2st64_b32 v191, v36, v37 offset0:36 offset1:54
	v_cvt_pk_f16_f32 v36, v74, v75
	v_cvt_pk_f16_f32 v37, v76, v77
	ds_write2st64_b32 v191, v36, v37 offset0:72 offset1:90
	v_cvt_f16_f32_e32 v36, v68
	v_pk_mul_f32 v[66:67], v[0:1], v[66:67]
	v_cvt_f16_f32_e32 v37, v69
	v_cvt_f16_f32_e32 v64, v66
	v_cvt_f16_f32_e32 v65, v67
	ds_write_b16 v180, v36 offset:6
	ds_write_b16 v180, v37 offset:46
	ds_write_b16 v180, v64 offset:5126
	ds_write_b16 v180, v65 offset:5166
	s_waitcnt lgkmcnt(7)
	ds_write_b16 v180, v78 offset:10246
	v_perm_b32 v36, v82, v84, s35
	v_perm_b32 v37, v78, v80, s35
	ds_write_b64 v180, v[36:37] offset:10280

.LBB0_1028:
	s_andn2_b64 vcc, exec, s[24:25]
	s_mov_b64 s[26:27], -1
	s_cbranch_vccnz .LBB0_1036
	s_and_b32 s26, s76, 1
	v_lshl_add_u32 v0, s26, 13, v229
	v_add_u32_e32 v68, 0x800, v0
	ds_read2_b64 v[36:39], v0 offset1:32
	ds_read2_b64 v[72:75], v0 offset0:64 offset1:96
	ds_read2_b64 v[76:79], v0 offset0:128 offset1:160
	ds_read2_b64 v[80:83], v0 offset0:192 offset1:224
	ds_read2_b64 v[84:87], v68 offset1:32
	ds_read2_b64 v[88:91], v68 offset0:64 offset1:96
	ds_read2_b64 v[92:95], v68 offset0:128 offset1:160
	ds_read2_b64 v[96:99], v68 offset0:192 offset1:224
	v_mad_u32_u24 v2, s26, v167, v230
	s_waitcnt lgkmcnt(7)
	v_pk_mul_f32 v[66:67], v[36:37], v[38:39]
	s_waitcnt lgkmcnt(6)
	v_pk_mul_f32 v[64:65], v[66:67], v[72:73]
	s_nop 0
	v_pk_mul_f32 v[60:61], v[64:65], v[74:75]
	s_waitcnt lgkmcnt(5)
	v_pk_mul_f32 v[54:55], v[60:61], v[76:77]
	s_nop 0
	v_pk_mul_f32 v[48:49], v[54:55], v[78:79]
	s_waitcnt lgkmcnt(4)
	v_pk_mul_f32 v[44:45], v[48:49], v[80:81]
	s_nop 0
	v_pk_mul_f32 v[38:39], v[44:45], v[82:83]
	s_waitcnt lgkmcnt(3)
	v_pk_mul_f32 v[58:59], v[38:39], v[84:85]
	v_rcp_f32_e32 v40, v38
	v_pk_mul_f32 v[50:51], v[58:59], v[86:87]
	s_waitcnt lgkmcnt(2)
	v_pk_mul_f32 v[46:47], v[50:51], v[88:89]
	v_rcp_f32_e32 v41, v39
	v_pk_mul_f32 v[42:43], v[46:47], v[90:91]
	s_waitcnt lgkmcnt(1)
	v_pk_mul_f32 v[62:63], v[42:43], v[92:93]
	s_nop 0
	v_pk_mul_f32 v[56:57], v[62:63], v[94:95]
	s_waitcnt lgkmcnt(0)
	v_pk_mul_f32 v[52:53], v[56:57], v[96:97]
	s_nop 0
	v_pk_mul_f32 v[0:1], v[52:53], v[98:99]
	s_and_saveexec_b64 s[26:27], s[4:5]
	s_cbranch_execz .LBB0_1031
	v_lshl_add_u32 v74, v175, 1, v2
	ds_read2st64_b32 v[72:73], v74 offset0:96 offset1:112
	ds_read2st64_b32 v[68:69], v74 offset0:64 offset1:80
	v_rcp_f32_e32 v70, v36
	v_rcp_f32_e32 v71, v37
	ds_read_b32 v84, v74 offset:32768
	s_waitcnt lgkmcnt(2)
	v_cvt_f32_f16_e32 v78, v73
	v_cvt_f32_f16_sdwa v79, v73 dst_sel:DWORD dst_unused:UNUSED_PAD src0_sel:WORD_1
	s_waitcnt lgkmcnt(1)
	v_cvt_f32_f16_e32 v74, v68
	v_cvt_f32_f16_sdwa v75, v68 dst_sel:DWORD dst_unused:UNUSED_PAD src0_sel:WORD_1
	v_cvt_f32_f16_e32 v76, v72
	v_cvt_f32_f16_sdwa v77, v72 dst_sel:DWORD dst_unused:UNUSED_PAD src0_sel:WORD_1
	v_cvt_f32_f16_e32 v72, v69
	v_cvt_f32_f16_sdwa v73, v69 dst_sel:DWORD dst_unused:UNUSED_PAD src0_sel:WORD_1
	v_pk_mul_f32 v[78:79], v[36:37], v[78:79]
	v_pk_mul_f32 v[76:77], v[70:71], v[76:77]
	v_pk_mul_f32 v[70:71], v[70:71], v[74:75]
	v_pk_mul_f32 v[72:73], v[40:41], v[72:73]
	v_pk_mul_f32 v[74:75], v[40:41], v[78:79]
	v_cvt_pk_f16_f32 v68, v78, v79
	v_pk_mul_f32 v[80:81], v[38:39], v[76:77]
	v_pk_mul_f32 v[82:83], v[38:39], v[70:71]
	ds_write2st64_b32 v181, v69, v68 offset1:18
	v_cvt_pk_f16_f32 v68, v72, v73
	v_cvt_pk_f16_f32 v69, v74, v75
	v_pk_mul_f32 v[76:77], v[0:1], v[76:77]
	ds_write2st64_b32 v181, v68, v69 offset0:36 offset1:54
	v_cvt_pk_f16_f32 v68, v80, v81
	v_cvt_pk_f16_f32 v69, v82, v83
	ds_write2st64_b32 v181, v68, v69 offset0:72 offset1:90
	v_cvt_f16_f32_e32 v68, v76
	v_pk_mul_f32 v[70:71], v[0:1], v[70:71]
	v_cvt_f16_f32_e32 v69, v77
	v_cvt_f16_f32_e32 v70, v70
	v_cvt_f16_f32_e32 v71, v71
	ds_write_b16 v176, v68
	ds_write_b16 v176, v69 offset:40
	ds_write_b16 v176, v70 offset:5120
	ds_write_b16 v176, v71 offset:5160
	s_waitcnt lgkmcnt(7)
	ds_write_b16 v176, v84 offset:10240
	v_lshl_add_u32 v74, v182, 1, v2
	ds_read2st64_b32 v[68:69], v74 offset0:64 offset1:80
	ds_read2st64_b32 v[72:73], v74 offset0:96 offset1:112
	ds_read_b32 v82, v74 offset:32768
	v_rcp_f32_e32 v70, v66
	v_rcp_f32_e32 v71, v67
	s_waitcnt lgkmcnt(2)
	v_cvt_f32_f16_e32 v76, v69
	v_cvt_f32_f16_sdwa v77, v69 dst_sel:DWORD dst_unused:UNUSED_PAD src0_sel:WORD_1
	s_waitcnt lgkmcnt(1)
	v_cvt_f32_f16_e32 v80, v73
	v_cvt_f32_f16_sdwa v81, v73 dst_sel:DWORD dst_unused:UNUSED_PAD src0_sel:WORD_1
	v_cvt_f32_f16_e32 v74, v68
	v_cvt_f32_f16_e32 v78, v72
	v_cvt_f32_f16_sdwa v79, v72 dst_sel:DWORD dst_unused:UNUSED_PAD src0_sel:WORD_1
	v_cvt_f32_f16_sdwa v75, v68 dst_sel:DWORD dst_unused:UNUSED_PAD src0_sel:WORD_1
	v_pk_mul_f32 v[36:37], v[36:37], v[76:77]
	v_pk_mul_f32 v[68:69], v[66:67], v[80:81]
	v_pk_mul_f32 v[72:73], v[70:71], v[78:79]
	v_pk_mul_f32 v[70:71], v[70:71], v[74:75]
	v_pk_mul_f32 v[74:75], v[40:41], v[36:37]
	v_pk_mul_f32 v[76:77], v[40:41], v[68:69]
	v_cvt_pk_f16_f32 v36, v36, v37
	v_cvt_pk_f16_f32 v37, v68, v69
	v_pk_mul_f32 v[78:79], v[38:39], v[72:73]
	v_pk_mul_f32 v[80:81], v[38:39], v[70:71]
	ds_write2st64_b32 v183, v36, v37 offset1:18
	v_cvt_pk_f16_f32 v36, v74, v75
	v_cvt_pk_f16_f32 v37, v76, v77
	v_pk_mul_f32 v[72:73], v[0:1], v[72:73]
	ds_write2st64_b32 v183, v36, v37 offset0:36 offset1:54
	v_cvt_pk_f16_f32 v36, v78, v79
	v_cvt_pk_f16_f32 v37, v80, v81
	ds_write2st64_b32 v183, v36, v37 offset0:72 offset1:90
	v_cvt_f16_f32_e32 v36, v72
	v_pk_mul_f32 v[70:71], v[0:1], v[70:71]
	v_cvt_f16_f32_e32 v37, v73
	v_cvt_f16_f32_e32 v68, v70
	v_cvt_f16_f32_e32 v69, v71
	ds_write_b16 v176, v36 offset:2
	ds_write_b16 v176, v37 offset:42
	ds_write_b16 v176, v68 offset:5122
	ds_write_b16 v176, v69 offset:5162
	s_waitcnt lgkmcnt(7)
	ds_write_b16 v176, v82 offset:10242
	v_lshl_add_u32 v72, v184, 1, v2
	ds_read2st64_b32 v[36:37], v72 offset0:64 offset1:80
	ds_read2st64_b32 v[70:71], v72 offset0:96 offset1:112
	ds_read_b32 v80, v72 offset:32768
	v_rcp_f32_e32 v68, v64
	v_rcp_f32_e32 v69, v65
	s_waitcnt lgkmcnt(2)
	v_cvt_f32_f16_e32 v74, v37
	v_cvt_f32_f16_sdwa v75, v37 dst_sel:DWORD dst_unused:UNUSED_PAD src0_sel:WORD_1
	s_waitcnt lgkmcnt(1)
	v_cvt_f32_f16_e32 v78, v71
	v_cvt_f32_f16_sdwa v79, v71 dst_sel:DWORD dst_unused:UNUSED_PAD src0_sel:WORD_1
	v_cvt_f32_f16_e32 v72, v36
	v_cvt_f32_f16_e32 v76, v70
	v_cvt_f32_f16_sdwa v77, v70 dst_sel:DWORD dst_unused:UNUSED_PAD src0_sel:WORD_1
	v_cvt_f32_f16_sdwa v73, v36 dst_sel:DWORD dst_unused:UNUSED_PAD src0_sel:WORD_1
	v_pk_mul_f32 v[36:37], v[66:67], v[74:75]
	v_pk_mul_f32 v[66:67], v[64:65], v[78:79]
	v_pk_mul_f32 v[70:71], v[68:69], v[76:77]
	v_pk_mul_f32 v[68:69], v[68:69], v[72:73]
	v_pk_mul_f32 v[72:73], v[40:41], v[36:37]
	v_pk_mul_f32 v[74:75], v[40:41], v[66:67]
	v_cvt_pk_f16_f32 v36, v36, v37
	v_cvt_pk_f16_f32 v37, v66, v67
	v_pk_mul_f32 v[76:77], v[38:39], v[70:71]
	v_pk_mul_f32 v[78:79], v[38:39], v[68:69]
	ds_write2st64_b32 v185, v36, v37 offset1:18
	v_cvt_pk_f16_f32 v36, v72, v73
	v_cvt_pk_f16_f32 v37, v74, v75
	v_pk_mul_f32 v[70:71], v[0:1], v[70:71]
	ds_write2st64_b32 v185, v36, v37 offset0:36 offset1:54
	v_cvt_pk_f16_f32 v36, v76, v77
	v_cvt_pk_f16_f32 v37, v78, v79
	ds_write2st64_b32 v185, v36, v37 offset0:72 offset1:90
	v_cvt_f16_f32_e32 v36, v70
	v_pk_mul_f32 v[68:69], v[0:1], v[68:69]
	v_cvt_f16_f32_e32 v37, v71
	v_cvt_f16_f32_e32 v66, v68
	v_cvt_f16_f32_e32 v67, v69
	ds_write_b16 v176, v36 offset:4
	ds_write_b16 v176, v37 offset:44
	ds_write_b16 v176, v66 offset:5124
	ds_write_b16 v176, v67 offset:5164
	s_waitcnt lgkmcnt(7)
	ds_write_b16 v176, v80 offset:10244
	v_lshl_add_u32 v70, v186, 1, v2
	ds_read2st64_b32 v[36:37], v70 offset0:64 offset1:80
	ds_read2st64_b32 v[68:69], v70 offset0:96 offset1:112
	ds_read_b32 v78, v70 offset:32768
	v_rcp_f32_e32 v66, v60
	v_rcp_f32_e32 v67, v61
	s_waitcnt lgkmcnt(2)
	v_cvt_f32_f16_e32 v72, v37
	v_cvt_f32_f16_sdwa v73, v37 dst_sel:DWORD dst_unused:UNUSED_PAD src0_sel:WORD_1
	s_waitcnt lgkmcnt(1)
	v_cvt_f32_f16_e32 v76, v69
	v_cvt_f32_f16_sdwa v77, v69 dst_sel:DWORD dst_unused:UNUSED_PAD src0_sel:WORD_1
	v_cvt_f32_f16_e32 v70, v36
	v_cvt_f32_f16_e32 v74, v68
	v_cvt_f32_f16_sdwa v75, v68 dst_sel:DWORD dst_unused:UNUSED_PAD src0_sel:WORD_1
	v_cvt_f32_f16_sdwa v71, v36 dst_sel:DWORD dst_unused:UNUSED_PAD src0_sel:WORD_1
	v_pk_mul_f32 v[36:37], v[64:65], v[72:73]
	v_pk_mul_f32 v[64:65], v[60:61], v[76:77]
	v_pk_mul_f32 v[68:69], v[66:67], v[74:75]
	v_pk_mul_f32 v[66:67], v[66:67], v[70:71]
	v_pk_mul_f32 v[70:71], v[40:41], v[36:37]
	v_pk_mul_f32 v[72:73], v[40:41], v[64:65]
	v_cvt_pk_f16_f32 v36, v36, v37
	v_cvt_pk_f16_f32 v37, v64, v65
	v_pk_mul_f32 v[74:75], v[38:39], v[68:69]
	v_pk_mul_f32 v[76:77], v[38:39], v[66:67]
	ds_write2st64_b32 v187, v36, v37 offset1:18
	v_cvt_pk_f16_f32 v36, v70, v71
	v_cvt_pk_f16_f32 v37, v72, v73
	v_pk_mul_f32 v[68:69], v[0:1], v[68:69]
	ds_write2st64_b32 v187, v36, v37 offset0:36 offset1:54
	v_cvt_pk_f16_f32 v36, v74, v75
	v_cvt_pk_f16_f32 v37, v76, v77
	ds_write2st64_b32 v187, v36, v37 offset0:72 offset1:90
	v_cvt_f16_f32_e32 v36, v68
	v_pk_mul_f32 v[66:67], v[0:1], v[66:67]
	v_cvt_f16_f32_e32 v37, v69
	v_cvt_f16_f32_e32 v64, v66
	v_cvt_f16_f32_e32 v65, v67
	ds_write_b16 v176, v36 offset:6
	ds_write_b16 v176, v37 offset:46
	ds_write_b16 v176, v64 offset:5126
	ds_write_b16 v176, v65 offset:5166
	s_waitcnt lgkmcnt(7)
	ds_write_b16 v176, v78 offset:10246
	v_perm_b32 v36, v82, v84, s35
	v_perm_b32 v37, v78, v80, s35
	ds_write_b64 v176, v[36:37] offset:10280
